# GEMM loop: LDS-DMA global loads issued first in each memory cluster, fragment ds_reads after them
# baseline (speedup 1.0000x reference)
; #define PG8_STAGE(bufoff, gbase, voff) do { _Pragma("unroll") for (int _i = 0; _i < 2; ++_i) \
;         __builtin_amdgcn_global_load_lds((const unsigned*)((const char*)(gbase) + (voff)[_i]), (LAS unsigned*)(lds + (bufoff) + ldsw + _i * 8192), 16, 0, 0); } while (0)
; #define PG8_LDA(dst, b, h) do { _Pragma("unroll") for (int m = 0; m < 4; ++m) _Pragma("unroll") for (int k = 0; k < 2; ++k) dst[m][k] = *(const LAS h16x8*)(lds + PG8_SA(b, h) + aoff + m * 2048 + k * 1024); } while (0)
; #define PG8_LDB(dst, b, h) do { _Pragma("unroll") for (int n = 0; n < 2; ++n) _Pragma("unroll") for (int k = 0; k < 2; ++k) dst[n][k] = *(const LAS h16x8*)(lds + PG8_SB(b, h) + boff + n * 2048 + k * 1024); } while (0)
; #define PG8_MMA(ai, bj, At, Bt) do { __builtin_amdgcn_s_setprio(1); _Pragma("unroll") for (int m = 0; m < 4; ++m) _Pragma("unroll") for (int n = 0; n < 2; ++n) _Pragma("unroll") for (int k = 0; k < 2; ++k) \
;         acc[ai][bj][m][n] = __builtin_amdgcn_mfma_f32_16x16x32_f16(Bt[n][k], At[m][k], acc[ai][bj][m][n], 0, 0, 0); __builtin_amdgcn_s_setprio(0); } while (0)
; #define PG8_WAIT_V(n) asm volatile("s_waitcnt vmcnt(" #n ")" ::: "memory")
; #define PG8_WAIT_L(n) asm volatile("s_waitcnt lgkmcnt(" #n ")" ::: "memory")
; #define PG8_BAR __builtin_amdgcn_s_barrier()
; #define PG8_SCHED __builtin_amdgcn_sched_barrier(0)
; __device__ __forceinline__ void gemm_phase(LAS unsigned char* lds, const Gemm g, const StaticOrder& S, const Epi& E) {
;     ...
;             PG8_LDB(B0, 0, 0); PG8_SCHED; PG8_LDA(At, 0, 0); PG8_STAGE(PG8_SA(1, 1), a1 + hstepA, voffA);
;             PG8_WAIT_L(8); PG8_BAR; PG8_WAIT_L(0); PG8_MMA(0, 0, At, B0); PG8_BAR; PG8_SCHED;
;             PG8_LDB(B1, 0, 1); PG8_STAGE(PG8_SB(0, 0), b2, voffB);
;             PG8_BAR; PG8_WAIT_L(0); PG8_MMA(0, 1, At, B1); PG8_BAR;
;             PG8_LDA(At, 0, 1); PG8_STAGE(PG8_SA(0, 0), a2, voffA);
;             PG8_BAR; PG8_WAIT_L(0); PG8_MMA(1, 0, At, B0); PG8_BAR; PG8_SCHED;
;             PG8_STAGE(PG8_SB(0, 1), b2 + hstepB, voffB);
;             PG8_WAIT_V(6); PG8_BAR; PG8_MMA(1, 1, At, B1); PG8_BAR;
.Lprio_skip:
.LBB0_762:
	s_cmp_gt_u32 s34, 15
	s_cselect_b64 s[36:37], -1, 0
	s_and_b64 s[36:37], s[6:7], s[36:37]
	s_and_b64 s[36:37], s[36:37], exec
	s_cselect_b32 s42, 0xfffff000, 0
	s_cselect_b32 s43, -1, 0
	s_add_i32 m0, s58, 0xc000
	s_add_u32 s86, s0, s42
	s_addc_u32 s87, s1, s43
	global_load_lds_dwordx4 v212, s[86:87]
	s_add_i32 m0, s58, 0xe000
	s_add_i32 s38, s34, 2
	global_load_lds_dwordx4 v214, s[86:87]
	ds_read_b128 v[128:131], v224
	ds_read_b128 v[132:135], v224 offset:1024
	ds_read_b128 v[136:139], v224 offset:2048
	ds_read_b128 v[140:143], v224 offset:3072
	s_cmp_gt_u32 s34, 13
	s_cselect_b64 s[36:37], -1, 0
	s_and_b64 s[36:37], s[6:7], s[36:37]
	s_and_b64 s[36:37], s[36:37], exec
	s_cselect_b32 s36, 0xfffff000, 0
	s_cselect_b32 s35, -1, 0
	s_add_u32 s36, s0, s36
	s_addc_u32 s35, s1, s35
	s_add_u32 s36, s36, 0x80
	s_addc_u32 s35, s35, 0
	s_cmp_eq_u32 s66, s34
	s_cselect_b32 s34, s4, s36
	s_cselect_b32 s35, s5, s35
	s_cselect_b32 s37, s29, s33
	s_cselect_b32 s36, s28, s27
	ds_read_b128 v[144:147], v239
	ds_read_b128 v[148:151], v239 offset:1024
	ds_read_b128 v[152:155], v239 offset:2048
	ds_read_b128 v[156:159], v239 offset:3072
	ds_read_b128 v[160:163], v239 offset:4096
	ds_read_b128 v[164:167], v239 offset:5120
	ds_read_b128 v[168:171], v239 offset:6144
	ds_read_b128 v[172:175], v239 offset:7168
	s_waitcnt lgkmcnt(8)
	s_barrier
	s_waitcnt lgkmcnt(0)
	s_waitcnt lgkmcnt(0)
	v_mfma_f32_16x16x32_f16 v[124:127], v[128:131], v[144:147], v[124:127]
	v_mfma_f32_16x16x32_f16 v[120:123], v[136:139], v[144:147], v[120:123]
	v_mfma_f32_16x16x32_f16 v[108:111], v[128:131], v[152:155], v[108:111]
	v_mfma_f32_16x16x32_f16 v[104:107], v[136:139], v[152:155], v[104:107]
	v_mfma_f32_16x16x32_f16 v[92:95], v[128:131], v[160:163], v[92:95]
	v_mfma_f32_16x16x32_f16 v[88:91], v[136:139], v[160:163], v[88:91]
	v_mfma_f32_16x16x32_f16 v[76:79], v[128:131], v[168:171], v[76:79]
	v_mfma_f32_16x16x32_f16 v[72:75], v[136:139], v[168:171], v[72:75]
	v_mfma_f32_16x16x32_f16 v[124:127], v[132:135], v[148:151], v[124:127]
	v_mfma_f32_16x16x32_f16 v[120:123], v[140:143], v[148:151], v[120:123]
	v_mfma_f32_16x16x32_f16 v[108:111], v[132:135], v[156:159], v[108:111]
	v_mfma_f32_16x16x32_f16 v[104:107], v[140:143], v[156:159], v[104:107]
	v_mfma_f32_16x16x32_f16 v[92:95], v[132:135], v[164:167], v[92:95]
	v_mfma_f32_16x16x32_f16 v[88:91], v[140:143], v[164:167], v[88:91]
	v_mfma_f32_16x16x32_f16 v[76:79], v[132:135], v[172:175], v[76:79]
	v_mfma_f32_16x16x32_f16 v[72:75], v[140:143], v[172:175], v[72:75]
	s_barrier
	s_add_i32 m0, s31, 0x10000
	s_add_u32 s86, s36, 0x80
	s_addc_u32 s87, s37, 0
	global_load_lds_dwordx4 v206, s[36:37]
	s_add_i32 m0, s31, 0x12000
	s_nop 0
	global_load_lds_dwordx4 v210, s[36:37]
	ds_read_b128 v[176:179], v225
	ds_read_b128 v[180:183], v225 offset:1024
	ds_read_b128 v[184:187], v225 offset:2048
	ds_read_b128 v[188:191], v225 offset:3072
	s_barrier
	s_waitcnt lgkmcnt(0)
	s_waitcnt lgkmcnt(0)
	v_mfma_f32_16x16x32_f16 v[116:119], v[176:179], v[144:147], v[116:119]
	v_mfma_f32_16x16x32_f16 v[112:115], v[184:187], v[144:147], v[112:115]
	v_mfma_f32_16x16x32_f16 v[100:103], v[176:179], v[152:155], v[100:103]
	v_mfma_f32_16x16x32_f16 v[96:99], v[184:187], v[152:155], v[96:99]
	v_mfma_f32_16x16x32_f16 v[84:87], v[176:179], v[160:163], v[84:87]
	v_mfma_f32_16x16x32_f16 v[80:83], v[184:187], v[160:163], v[80:83]
	v_mfma_f32_16x16x32_f16 v[68:71], v[176:179], v[168:171], v[68:71]
	v_mfma_f32_16x16x32_f16 v[64:67], v[184:187], v[168:171], v[64:67]
	v_mfma_f32_16x16x32_f16 v[116:119], v[180:183], v[148:151], v[116:119]
	v_mfma_f32_16x16x32_f16 v[112:115], v[188:191], v[148:151], v[112:115]
	v_mfma_f32_16x16x32_f16 v[100:103], v[180:183], v[156:159], v[100:103]
	v_mfma_f32_16x16x32_f16 v[96:99], v[188:191], v[156:159], v[96:99]
	v_mfma_f32_16x16x32_f16 v[84:87], v[180:183], v[164:167], v[84:87]
	v_mfma_f32_16x16x32_f16 v[80:83], v[188:191], v[164:167], v[80:83]
	v_mfma_f32_16x16x32_f16 v[68:71], v[180:183], v[172:175], v[68:71]
	v_mfma_f32_16x16x32_f16 v[64:67], v[188:191], v[172:175], v[64:67]
	s_mov_b32 m0, s58
	s_add_u32 s88, s34, 0x80
	s_addc_u32 s89, s35, 0
	s_barrier
	global_load_lds_dwordx4 v204, s[34:35]
	s_mov_b32 m0, s59
	s_nop 0
	global_load_lds_dwordx4 v208, s[34:35]
	ds_read_b128 v[144:147], v239 offset:16384
	ds_read_b128 v[148:151], v239 offset:17408
	ds_read_b128 v[152:155], v239 offset:18432
	ds_read_b128 v[156:159], v239 offset:19456
	ds_read_b128 v[160:163], v239 offset:20480
	ds_read_b128 v[164:167], v239 offset:21504
	ds_read_b128 v[168:171], v239 offset:22528
	ds_read_b128 v[172:175], v239 offset:23552
	s_barrier
	s_waitcnt lgkmcnt(0)
	s_waitcnt lgkmcnt(0)
	v_mfma_f32_16x16x32_f16 v[60:63], v[128:131], v[144:147], v[60:63]
	v_mfma_f32_16x16x32_f16 v[56:59], v[136:139], v[144:147], v[56:59]
	v_mfma_f32_16x16x32_f16 v[44:47], v[128:131], v[152:155], v[44:47]
	v_mfma_f32_16x16x32_f16 v[40:43], v[136:139], v[152:155], v[40:43]
	v_mfma_f32_16x16x32_f16 v[28:31], v[128:131], v[160:163], v[28:31]
	v_mfma_f32_16x16x32_f16 v[24:27], v[136:139], v[160:163], v[24:27]
	v_mfma_f32_16x16x32_f16 v[12:15], v[128:131], v[168:171], v[12:15]
	v_mfma_f32_16x16x32_f16 v[8:11], v[136:139], v[168:171], v[8:11]
	v_mfma_f32_16x16x32_f16 v[60:63], v[132:135], v[148:151], v[60:63]
	v_mfma_f32_16x16x32_f16 v[56:59], v[140:143], v[148:151], v[56:59]
	v_mfma_f32_16x16x32_f16 v[44:47], v[132:135], v[156:159], v[44:47]
	v_mfma_f32_16x16x32_f16 v[40:43], v[140:143], v[156:159], v[40:43]
	v_mfma_f32_16x16x32_f16 v[28:31], v[132:135], v[164:167], v[28:31]
	v_mfma_f32_16x16x32_f16 v[24:27], v[140:143], v[164:167], v[24:27]
	v_mfma_f32_16x16x32_f16 v[12:15], v[132:135], v[172:175], v[12:15]
	v_mfma_f32_16x16x32_f16 v[8:11], v[140:143], v[172:175], v[8:11]
	s_barrier
; #define PG8_STAGE(bufoff, gbase, voff) do { _Pragma("unroll") for (int _i = 0; _i < 2; ++_i) \
;         __builtin_amdgcn_global_load_lds((const unsigned*)((const char*)(gbase) + (voff)[_i]), (LAS unsigned*)(lds + (bufoff) + ldsw + _i * 8192), 16, 0, 0); } while (0)
; #define PG8_LDA(dst, b, h) do { _Pragma("unroll") for (int m = 0; m < 4; ++m) _Pragma("unroll") for (int k = 0; k < 2; ++k) dst[m][k] = *(const LAS h16x8*)(lds + PG8_SA(b, h) + aoff + m * 2048 + k * 1024); } while (0)
; #define PG8_LDB(dst, b, h) do { _Pragma("unroll") for (int n = 0; n < 2; ++n) _Pragma("unroll") for (int k = 0; k < 2; ++k) dst[n][k] = *(const LAS h16x8*)(lds + PG8_SB(b, h) + boff + n * 2048 + k * 1024); } while (0)
; #define PG8_MMA(ai, bj, At, Bt) do { __builtin_amdgcn_s_setprio(1); _Pragma("unroll") for (int m = 0; m < 4; ++m) _Pragma("unroll") for (int n = 0; n < 2; ++n) _Pragma("unroll") for (int k = 0; k < 2; ++k) \
;         acc[ai][bj][m][n] = __builtin_amdgcn_mfma_f32_16x16x32_f16(Bt[n][k], At[m][k], acc[ai][bj][m][n], 0, 0, 0); __builtin_amdgcn_s_setprio(0); } while (0)
; #define PG8_WAIT_V(n) asm volatile("s_waitcnt vmcnt(" #n ")" ::: "memory")
; #define PG8_WAIT_L(n) asm volatile("s_waitcnt lgkmcnt(" #n ")" ::: "memory")
; #define PG8_BAR __builtin_amdgcn_s_barrier()
; #define PG8_SCHED __builtin_amdgcn_sched_barrier(0)
; __device__ __forceinline__ void gemm_phase(LAS unsigned char* lds, const Gemm g, const StaticOrder& S, const Epi& E) {
;     ...
;             PG8_WAIT_V(6); PG8_BAR; PG8_MMA(1, 1, At, B1); PG8_BAR;
;             PG8_LDB(B0, 1, 0); PG8_SCHED; PG8_LDA(At, 1, 0); PG8_STAGE(PG8_SA(0, 1), a2 + hstepA, voffA);
;             PG8_WAIT_L(8); PG8_BAR; PG8_WAIT_L(0); PG8_MMA(0, 0, At, B0); PG8_BAR; PG8_SCHED;
;             PG8_LDB(B1, 1, 1); PG8_STAGE(PG8_SB(1, 0), b3, voffB);
;             PG8_BAR; PG8_WAIT_L(0); PG8_MMA(0, 1, At, B1); PG8_BAR;
;             PG8_LDA(At, 1, 1); PG8_STAGE(PG8_SA(1, 0), a3, voffA);
	s_add_u32 s36, s36, s18
	s_addc_u32 s37, s37, s19
	s_add_u32 s96, s36, 0x80
	s_addc_u32 s97, s37, 0
	s_add_i32 m0, s31, 0x14000
	s_nop 0
	global_load_lds_dwordx4 v206, s[36:37]
	s_add_i32 m0, s31, 0x16000
	s_nop 0
	global_load_lds_dwordx4 v210, s[36:37]
	s_waitcnt vmcnt(6)
	s_barrier
	v_mfma_f32_16x16x32_f16 v[52:55], v[176:179], v[144:147], v[52:55]
	v_mfma_f32_16x16x32_f16 v[48:51], v[184:187], v[144:147], v[48:51]
	v_mfma_f32_16x16x32_f16 v[36:39], v[176:179], v[152:155], v[36:39]
	v_mfma_f32_16x16x32_f16 v[32:35], v[184:187], v[152:155], v[32:35]
	v_mfma_f32_16x16x32_f16 v[20:23], v[176:179], v[160:163], v[20:23]
	v_mfma_f32_16x16x32_f16 v[16:19], v[184:187], v[160:163], v[16:19]
	v_mfma_f32_16x16x32_f16 v[4:7], v[176:179], v[168:171], v[4:7]
	v_mfma_f32_16x16x32_f16 v[0:3], v[184:187], v[168:171], v[0:3]
	v_mfma_f32_16x16x32_f16 v[52:55], v[180:183], v[148:151], v[52:55]
	v_mfma_f32_16x16x32_f16 v[48:51], v[188:191], v[148:151], v[48:51]
	v_mfma_f32_16x16x32_f16 v[36:39], v[180:183], v[156:159], v[36:39]
	v_mfma_f32_16x16x32_f16 v[32:35], v[188:191], v[156:159], v[32:35]
	v_mfma_f32_16x16x32_f16 v[20:23], v[180:183], v[164:167], v[20:23]
	v_mfma_f32_16x16x32_f16 v[16:19], v[188:191], v[164:167], v[16:19]
	v_mfma_f32_16x16x32_f16 v[4:7], v[180:183], v[172:175], v[4:7]
	v_mfma_f32_16x16x32_f16 v[0:3], v[188:191], v[172:175], v[0:3]
	s_barrier
	s_mov_b32 m0, s60
	s_add_u32 s34, s34, s16
	s_addc_u32 s35, s35, s17
	global_load_lds_dwordx4 v204, s[34:35]
	s_mov_b32 m0, s61
	s_nop 0
	global_load_lds_dwordx4 v208, s[34:35]
	ds_read_b128 v[128:131], v241
	ds_read_b128 v[132:135], v241 offset:1024
	ds_read_b128 v[136:139], v241 offset:2048
	ds_read_b128 v[140:143], v241 offset:3072
	ds_read_b128 v[144:147], v239 offset:32768
	ds_read_b128 v[148:151], v239 offset:33792
	ds_read_b128 v[152:155], v239 offset:34816
	ds_read_b128 v[156:159], v239 offset:35840
	ds_read_b128 v[160:163], v239 offset:36864
	ds_read_b128 v[164:167], v239 offset:37888
	ds_read_b128 v[168:171], v239 offset:38912
	ds_read_b128 v[172:175], v239 offset:39936
	s_waitcnt lgkmcnt(8)
	s_barrier
	s_waitcnt lgkmcnt(0)
	s_waitcnt lgkmcnt(0)
	v_mfma_f32_16x16x32_f16 v[124:127], v[128:131], v[144:147], v[124:127]
	v_mfma_f32_16x16x32_f16 v[120:123], v[136:139], v[144:147], v[120:123]
	v_mfma_f32_16x16x32_f16 v[108:111], v[128:131], v[152:155], v[108:111]
	v_mfma_f32_16x16x32_f16 v[104:107], v[136:139], v[152:155], v[104:107]
	v_mfma_f32_16x16x32_f16 v[92:95], v[128:131], v[160:163], v[92:95]
	v_mfma_f32_16x16x32_f16 v[88:91], v[136:139], v[160:163], v[88:91]
	v_mfma_f32_16x16x32_f16 v[76:79], v[128:131], v[168:171], v[76:79]
	v_mfma_f32_16x16x32_f16 v[72:75], v[136:139], v[168:171], v[72:75]
	v_mfma_f32_16x16x32_f16 v[124:127], v[132:135], v[148:151], v[124:127]
	v_mfma_f32_16x16x32_f16 v[120:123], v[140:143], v[148:151], v[120:123]
	v_mfma_f32_16x16x32_f16 v[108:111], v[132:135], v[156:159], v[108:111]
	v_mfma_f32_16x16x32_f16 v[104:107], v[140:143], v[156:159], v[104:107]
	v_mfma_f32_16x16x32_f16 v[92:95], v[132:135], v[164:167], v[92:95]
	v_mfma_f32_16x16x32_f16 v[88:91], v[140:143], v[164:167], v[88:91]
	v_mfma_f32_16x16x32_f16 v[76:79], v[132:135], v[172:175], v[76:79]
	v_mfma_f32_16x16x32_f16 v[72:75], v[140:143], v[172:175], v[72:75]
	s_barrier
	s_add_i32 m0, s31, 0x18000
	s_nop 0
	global_load_lds_dwordx4 v206, s[86:87]
	s_add_i32 m0, s31, 0x1a000
	s_nop 0
	global_load_lds_dwordx4 v210, s[86:87]
	ds_read_b128 v[176:179], v248
	ds_read_b128 v[180:183], v248 offset:1024
	ds_read_b128 v[184:187], v248 offset:2048
	ds_read_b128 v[188:191], v248 offset:3072
	s_barrier
; #define PG8_STAGE(bufoff, gbase, voff) do { _Pragma("unroll") for (int _i = 0; _i < 2; ++_i) \
;         __builtin_amdgcn_global_load_lds((const unsigned*)((const char*)(gbase) + (voff)[_i]), (LAS unsigned*)(lds + (bufoff) + ldsw + _i * 8192), 16, 0, 0); } while (0)
; #define PG8_LDA(dst, b, h) do { _Pragma("unroll") for (int m = 0; m < 4; ++m) _Pragma("unroll") for (int k = 0; k < 2; ++k) dst[m][k] = *(const LAS h16x8*)(lds + PG8_SA(b, h) + aoff + m * 2048 + k * 1024); } while (0)
; #define PG8_MMA(ai, bj, At, Bt) do { __builtin_amdgcn_s_setprio(1); _Pragma("unroll") for (int m = 0; m < 4; ++m) _Pragma("unroll") for (int n = 0; n < 2; ++n) _Pragma("unroll") for (int k = 0; k < 2; ++k) \
;         acc[ai][bj][m][n] = __builtin_amdgcn_mfma_f32_16x16x32_f16(Bt[n][k], At[m][k], acc[ai][bj][m][n], 0, 0, 0); __builtin_amdgcn_s_setprio(0); } while (0)
; #define PG8_WAIT_V(n) asm volatile("s_waitcnt vmcnt(" #n ")" ::: "memory")
; #define PG8_WAIT_L(n) asm volatile("s_waitcnt lgkmcnt(" #n ")" ::: "memory")
; #define PG8_BAR __builtin_amdgcn_s_barrier()
; #define PG8_SCHED __builtin_amdgcn_sched_barrier(0)
; __device__ __forceinline__ void gemm_phase(LAS unsigned char* lds, const Gemm g, const StaticOrder& S, const Epi& E) {
;     ...
;             PG8_LDA(At, 1, 1); PG8_STAGE(PG8_SA(1, 0), a3, voffA);
;             PG8_BAR; PG8_WAIT_L(0); PG8_MMA(1, 0, At, B0); PG8_BAR; PG8_SCHED;
;             PG8_STAGE(PG8_SB(1, 1), b3 + hstepB, voffB);
;             PG8_WAIT_V(6); PG8_BAR; PG8_MMA(1, 1, At, B1); PG8_BAR;
	s_waitcnt lgkmcnt(0)
	s_waitcnt lgkmcnt(0)
	v_mfma_f32_16x16x32_f16 v[116:119], v[176:179], v[144:147], v[116:119]
	v_mfma_f32_16x16x32_f16 v[112:115], v[184:187], v[144:147], v[112:115]
	v_mfma_f32_16x16x32_f16 v[100:103], v[176:179], v[152:155], v[100:103]
	v_mfma_f32_16x16x32_f16 v[96:99], v[184:187], v[152:155], v[96:99]
	v_mfma_f32_16x16x32_f16 v[84:87], v[176:179], v[160:163], v[84:87]
	v_mfma_f32_16x16x32_f16 v[80:83], v[184:187], v[160:163], v[80:83]
	v_mfma_f32_16x16x32_f16 v[68:71], v[176:179], v[168:171], v[68:71]
	v_mfma_f32_16x16x32_f16 v[64:67], v[184:187], v[168:171], v[64:67]
	v_mfma_f32_16x16x32_f16 v[116:119], v[180:183], v[148:151], v[116:119]
	v_mfma_f32_16x16x32_f16 v[112:115], v[188:191], v[148:151], v[112:115]
	v_mfma_f32_16x16x32_f16 v[100:103], v[180:183], v[156:159], v[100:103]
	v_mfma_f32_16x16x32_f16 v[96:99], v[188:191], v[156:159], v[96:99]
	v_mfma_f32_16x16x32_f16 v[84:87], v[180:183], v[164:167], v[84:87]
	v_mfma_f32_16x16x32_f16 v[80:83], v[188:191], v[164:167], v[80:83]
	v_mfma_f32_16x16x32_f16 v[68:71], v[180:183], v[172:175], v[68:71]
	v_mfma_f32_16x16x32_f16 v[64:67], v[188:191], v[172:175], v[64:67]
	s_mov_b32 m0, s62
	s_barrier
	global_load_lds_dwordx4 v204, s[88:89]
	s_mov_b32 m0, s63
	s_nop 0
	global_load_lds_dwordx4 v208, s[88:89]
	ds_read_b128 v[144:147], v239 offset:49152
	ds_read_b128 v[148:151], v239 offset:50176
	ds_read_b128 v[152:155], v239 offset:51200
	ds_read_b128 v[156:159], v239 offset:52224
	ds_read_b128 v[160:163], v239 offset:53248
	ds_read_b128 v[164:167], v239 offset:54272
	ds_read_b128 v[168:171], v239 offset:55296
	ds_read_b128 v[172:175], v239 offset:56320
	s_barrier
	s_waitcnt lgkmcnt(0)
	s_waitcnt lgkmcnt(0)
	v_mfma_f32_16x16x32_f16 v[60:63], v[128:131], v[144:147], v[60:63]
	v_mfma_f32_16x16x32_f16 v[56:59], v[136:139], v[144:147], v[56:59]
	v_mfma_f32_16x16x32_f16 v[44:47], v[128:131], v[152:155], v[44:47]
	v_mfma_f32_16x16x32_f16 v[40:43], v[136:139], v[152:155], v[40:43]
	v_mfma_f32_16x16x32_f16 v[28:31], v[128:131], v[160:163], v[28:31]
	v_mfma_f32_16x16x32_f16 v[24:27], v[136:139], v[160:163], v[24:27]
	v_mfma_f32_16x16x32_f16 v[12:15], v[128:131], v[168:171], v[12:15]
	v_mfma_f32_16x16x32_f16 v[8:11], v[136:139], v[168:171], v[8:11]
	v_mfma_f32_16x16x32_f16 v[60:63], v[132:135], v[148:151], v[60:63]
	v_mfma_f32_16x16x32_f16 v[56:59], v[140:143], v[148:151], v[56:59]
	v_mfma_f32_16x16x32_f16 v[44:47], v[132:135], v[156:159], v[44:47]
	v_mfma_f32_16x16x32_f16 v[40:43], v[140:143], v[156:159], v[40:43]
	v_mfma_f32_16x16x32_f16 v[28:31], v[132:135], v[164:167], v[28:31]
	v_mfma_f32_16x16x32_f16 v[24:27], v[140:143], v[164:167], v[24:27]
	v_mfma_f32_16x16x32_f16 v[12:15], v[132:135], v[172:175], v[12:15]
	v_mfma_f32_16x16x32_f16 v[8:11], v[140:143], v[172:175], v[8:11]
	s_barrier
	s_add_i32 m0, s31, 0x1c000
	s_nop 0
	global_load_lds_dwordx4 v206, s[96:97]
	s_add_i32 m0, s31, 0x1e000
	s_nop 0
	global_load_lds_dwordx4 v210, s[96:97]
	s_waitcnt vmcnt(6)
	s_barrier
	v_mfma_f32_16x16x32_f16 v[52:55], v[176:179], v[144:147], v[52:55]
	v_mfma_f32_16x16x32_f16 v[48:51], v[184:187], v[144:147], v[48:51]
	v_mfma_f32_16x16x32_f16 v[36:39], v[176:179], v[152:155], v[36:39]
	v_mfma_f32_16x16x32_f16 v[32:35], v[184:187], v[152:155], v[32:35]
	v_mfma_f32_16x16x32_f16 v[20:23], v[176:179], v[160:163], v[20:23]
	v_mfma_f32_16x16x32_f16 v[16:19], v[184:187], v[160:163], v[16:19]
	v_mfma_f32_16x16x32_f16 v[4:7], v[176:179], v[168:171], v[4:7]
	v_mfma_f32_16x16x32_f16 v[0:3], v[184:187], v[168:171], v[0:3]
	v_mfma_f32_16x16x32_f16 v[52:55], v[180:183], v[148:151], v[52:55]
	v_mfma_f32_16x16x32_f16 v[48:51], v[188:191], v[148:151], v[48:51]
	v_mfma_f32_16x16x32_f16 v[36:39], v[180:183], v[156:159], v[36:39]
	v_mfma_f32_16x16x32_f16 v[32:35], v[188:191], v[156:159], v[32:35]
	v_mfma_f32_16x16x32_f16 v[20:23], v[180:183], v[164:167], v[20:23]
	v_mfma_f32_16x16x32_f16 v[16:19], v[188:191], v[164:167], v[16:19]
	v_mfma_f32_16x16x32_f16 v[4:7], v[180:183], v[172:175], v[4:7]
	v_mfma_f32_16x16x32_f16 v[0:3], v[188:191], v[172:175], v[0:3]
	s_add_u32 s0, s0, 0x100
	s_addc_u32 s1, s1, 0
	s_add_u32 s27, s27, 0x100
	s_addc_u32 s33, s33, 0
	s_cmp_ge_u32 s38, s64
	s_mov_b32 s34, s38
	s_barrier
	s_cbranch_scc0 .LBB0_762
	s_setprio 0
	s_lshl_b32 s0, s84, 8
	s_or_b32 s27, s0, s65
	v_lshl_add_u32 v240, s30, 8, v200
	v_or_b32_e32 v216, s27, v202
	s_cmp_eq_u32 s93, 3
	s_cbranch_scc1 .Lst16_fast
	s_cmp_eq_u32 s93, 1
	s_cbranch_scc0 .Llora_no
	s_lshr_b32 s0, s84, 2
	s_cmp_lt_u32 s0, 2
	s_cbranch_scc1 .Llora_fast
